# energy: P1 k_pe tiles (pn=7, 192 of 256 weight columns are zero padding) skip the bj=1 MFMA groups (exact: those accumulators are unused); mid-segment setprio pair replaced by the test
# speedup vs baseline: 1.0028x; 1.0028x over previous
; #define G_STAGE(bufoff, gbase, v0, v1) do { \
;         __builtin_amdgcn_global_load_lds((const unsigned*)((const char*)(gbase) + (v0)), (LAS unsigned*)(lds + (bufoff) + ldsw), 16, 0, 0); \
;         __builtin_amdgcn_global_load_lds((const unsigned*)((const char*)(gbase) + (v1)), (LAS unsigned*)(lds + (bufoff) + ldsw + 8192), 16, 0, 0); } while (0)
; #define G_LDA(dst, b, h) do { _Pragma("unroll") for (int m = 0; m < 4; ++m) _Pragma("unroll") for (int k = 0; k < 2; ++k) dst[m][k] = *(const LAS bf16x8*)(lds + G_SA(b, h) + aoff + m * 2048 + k * 1024); } while (0)
; #define G_LDB(dst, b, h) do { _Pragma("unroll") for (int n = 0; n < 2; ++n) _Pragma("unroll") for (int k = 0; k < 2; ++k) dst[n][k] = *(const LAS bf16x8*)(lds + G_SB(b, h) + boff + n * 2048 + k * 1024); } while (0)
; #define G_MMA(ai, bj, At, Bt) do { __builtin_amdgcn_s_setprio(1); _Pragma("unroll") for (int m = 0; m < 4; ++m) _Pragma("unroll") for (int n = 0; n < 2; ++n) _Pragma("unroll") for (int k = 0; k < 2; ++k) \
;         acc[ai][bj][m][n] = __builtin_amdgcn_mfma_f32_16x16x32_bf16(Bt[n][k], At[m][k], acc[ai][bj][m][n], 0, 0, 0); __builtin_amdgcn_s_setprio(0); } while (0)
; #define G_WAIT_V(n) asm volatile("s_waitcnt vmcnt(" #n ")" ::: "memory")
; #define G_WAIT_L(n) asm volatile("s_waitcnt lgkmcnt(" #n ")" ::: "memory")
; #define G_BAR __builtin_amdgcn_s_barrier()
; #define G_SCHED __builtin_amdgcn_sched_barrier(0)
; template <class Epi, class Sched>
; __device__ __forceinline__ void gemm_phase(LAS unsigned char* lds, const Sched& S, const Epi& E) {
;     ...
;             const char* a1 = cA + (size_t)(t + 1) * kstep;
;             const char* a2 = last ? nA : cA + (size_t)(t + 2) * kstep; const char* b2 = last ? nB : cB + (size_t)(t + 2) * kstep;
;             const char* a3 = a2 + kstep; const char* b3 = b2 + kstep;
;             const unsigned v20 = last ? vn0 : vc0, v21 = last ? vn1 : vc1; const size_t h2 = last ? hAn : hAc;
;             G_LDB(B0, 0, 0); G_LDB(B1, 0, 1); G_SCHED; G_LDA(At, 0, 0); G_STAGE(G_SA(1, 1), a1 + hAc, vc0, vc1);
;             G_WAIT_V(8); G_WAIT_L(0); G_BAR; G_MMA(0, 0, At, B0); G_MMA(0, 1, At, B1); G_BAR; G_SCHED;
;             G_LDA(At, 0, 1); G_STAGE(G_SB(0, 0), b2, vb0, vb1); G_STAGE(G_SB(0, 1), b2 + hstepB, vb0, vb1); G_STAGE(G_SA(0, 0), a2, v20, v21);
;             G_WAIT_V(8); G_WAIT_L(0); G_BAR; G_MMA(1, 0, At, B0); G_MMA(1, 1, At, B1); G_BAR; G_SCHED;
.LBB0_184:
	ds_read_b128 v[150:153], v169
	ds_read_b128 v[154:157], v169 offset:1024
	ds_read_b128 v[158:161], v169 offset:2048
	ds_read_b128 v[162:165], v169 offset:3072
	ds_read_b128 v[178:181], v175
	ds_read_b128 v[182:185], v175 offset:1024
	ds_read_b128 v[186:189], v175 offset:2048
	ds_read_b128 v[190:193], v175 offset:3072
	s_add_u32 s12, s8, 0xfff80080
	s_addc_u32 s13, s9, -1
	s_cmp_eq_u32 s63, 28
	s_cselect_b32 s47, s7, s13
	s_cselect_b32 s46, s11, s12
	s_cselect_b32 s13, s38, s61
	s_cselect_b32 s12, s39, s50
	v_lshl_add_u64 v[210:211], s[8:9], 0, v[138:139]
	s_add_i32 m0, s25, 0xc000
	ds_read_b128 v[194:197], v176
	ds_read_b128 v[198:201], v176 offset:1024
	ds_read_b128 v[202:205], v176 offset:2048
	ds_read_b128 v[206:209], v176 offset:3072
	ds_read_b128 v[214:217], v176 offset:4096
	ds_read_b128 v[218:221], v176 offset:5120
	ds_read_b128 v[222:225], v176 offset:6144
	ds_read_b128 v[226:229], v176 offset:7168
	global_load_lds_dwordx4 v[210:211], off
	v_lshl_add_u64 v[210:211], s[8:9], 0, v[140:141]
	s_add_i32 m0, s25, 0xe000
	s_nop 0
	global_load_lds_dwordx4 v[210:211], off
	s_waitcnt vmcnt(8)
	s_waitcnt lgkmcnt(0)
	s_barrier
	s_setprio 1
	s_waitcnt lgkmcnt(0)
	v_mfma_f32_16x16x32_bf16 v[124:127], v[150:153], v[194:197], v[124:127]
	v_mfma_f32_16x16x32_bf16 v[120:123], v[158:161], v[194:197], v[120:123]
	v_mfma_f32_16x16x32_bf16 v[108:111], v[150:153], v[202:205], v[108:111]
	v_mfma_f32_16x16x32_bf16 v[104:107], v[158:161], v[202:205], v[104:107]
	v_mfma_f32_16x16x32_bf16 v[92:95], v[150:153], v[214:217], v[92:95]
	v_mfma_f32_16x16x32_bf16 v[88:91], v[158:161], v[214:217], v[88:91]
	v_mfma_f32_16x16x32_bf16 v[76:79], v[150:153], v[222:225], v[76:79]
	v_mfma_f32_16x16x32_bf16 v[72:75], v[158:161], v[222:225], v[72:75]
	v_mfma_f32_16x16x32_bf16 v[124:127], v[154:157], v[198:201], v[124:127]
	v_mfma_f32_16x16x32_bf16 v[120:123], v[162:165], v[198:201], v[120:123]
	v_mfma_f32_16x16x32_bf16 v[108:111], v[154:157], v[206:209], v[108:111]
	v_mfma_f32_16x16x32_bf16 v[104:107], v[162:165], v[206:209], v[104:107]
	v_mfma_f32_16x16x32_bf16 v[92:95], v[154:157], v[218:221], v[92:95]
	v_mfma_f32_16x16x32_bf16 v[88:91], v[162:165], v[218:221], v[88:91]
	v_mfma_f32_16x16x32_bf16 v[76:79], v[154:157], v[226:229], v[76:79]
	v_mfma_f32_16x16x32_bf16 v[72:75], v[162:165], v[226:229], v[72:75]
	s_cmp_eq_u32 s10, 7
	s_cbranch_scc1 .Lp1_skip0
	v_mfma_f32_16x16x32_bf16 v[116:119], v[178:181], v[194:197], v[116:119]
	v_mfma_f32_16x16x32_bf16 v[112:115], v[186:189], v[194:197], v[112:115]
	v_mfma_f32_16x16x32_bf16 v[100:103], v[178:181], v[202:205], v[100:103]
	v_mfma_f32_16x16x32_bf16 v[96:99], v[186:189], v[202:205], v[96:99]
	v_mfma_f32_16x16x32_bf16 v[84:87], v[178:181], v[214:217], v[84:87]
	v_mfma_f32_16x16x32_bf16 v[80:83], v[186:189], v[214:217], v[80:83]
	v_mfma_f32_16x16x32_bf16 v[68:71], v[178:181], v[222:225], v[68:71]
	v_mfma_f32_16x16x32_bf16 v[64:67], v[186:189], v[222:225], v[64:67]
	v_mfma_f32_16x16x32_bf16 v[116:119], v[182:185], v[198:201], v[116:119]
	v_mfma_f32_16x16x32_bf16 v[112:115], v[190:193], v[198:201], v[112:115]
	v_mfma_f32_16x16x32_bf16 v[100:103], v[182:185], v[206:209], v[100:103]
	v_mfma_f32_16x16x32_bf16 v[96:99], v[190:193], v[206:209], v[96:99]
	v_mfma_f32_16x16x32_bf16 v[84:87], v[182:185], v[218:221], v[84:87]
	v_mfma_f32_16x16x32_bf16 v[80:83], v[190:193], v[218:221], v[80:83]
	v_mfma_f32_16x16x32_bf16 v[68:71], v[182:185], v[226:229], v[68:71]
	v_mfma_f32_16x16x32_bf16 v[64:67], v[190:193], v[226:229], v[64:67]
.Lp1_skip0:
	s_setprio 0
	s_barrier
	s_add_i32 s68, s53, s24
	v_lshl_add_u64 v[210:211], s[12:13], 0, v[132:133]
	s_mov_b32 m0, s68
	ds_read_b128 v[194:197], v176 offset:16384
	ds_read_b128 v[198:201], v176 offset:17408
	ds_read_b128 v[202:205], v176 offset:18432
	ds_read_b128 v[206:209], v176 offset:19456
	ds_read_b128 v[214:217], v176 offset:20480
	ds_read_b128 v[218:221], v176 offset:21504
	ds_read_b128 v[222:225], v176 offset:22528
	ds_read_b128 v[226:229], v176 offset:23552
	global_load_lds_dwordx4 v[210:211], off
	s_add_i32 m0, s68, 0x2000
	s_add_u32 s68, s12, 0x80000
	v_lshl_add_u64 v[230:231], s[12:13], 0, v[134:135]
	s_addc_u32 s69, s13, 0
	s_add_i32 s70, s84, s24
	global_load_lds_dwordx4 v[230:231], off
	v_lshl_add_u64 v[232:233], s[68:69], 0, v[132:133]
	s_mov_b32 m0, s70
	v_lshl_add_u64 v[234:235], s[46:47], 0, v[134:135]
	global_load_lds_dwordx4 v[232:233], off
	v_lshl_add_u64 v[232:233], s[68:69], 0, v[134:135]
	s_add_i32 m0, s70, 0x2000
	s_nop 0
	global_load_lds_dwordx4 v[232:233], off
	v_lshl_add_u64 v[232:233], s[46:47], 0, v[132:133]
	s_mov_b32 m0, s25
	s_nop 0
	global_load_lds_dwordx4 v[232:233], off
	s_mov_b32 m0, s44
	s_nop 0
	global_load_lds_dwordx4 v[234:235], off
	s_waitcnt vmcnt(8)
	s_waitcnt lgkmcnt(0)
	s_barrier
	s_setprio 1
	s_waitcnt lgkmcnt(0)
	v_mfma_f32_16x16x32_bf16 v[60:63], v[150:153], v[194:197], v[60:63]
	v_mfma_f32_16x16x32_bf16 v[56:59], v[158:161], v[194:197], v[56:59]
	v_mfma_f32_16x16x32_bf16 v[44:47], v[150:153], v[202:205], v[44:47]
	v_mfma_f32_16x16x32_bf16 v[40:43], v[158:161], v[202:205], v[40:43]
	v_mfma_f32_16x16x32_bf16 v[28:31], v[150:153], v[214:217], v[28:31]
	v_mfma_f32_16x16x32_bf16 v[24:27], v[158:161], v[214:217], v[24:27]
	v_mfma_f32_16x16x32_bf16 v[12:15], v[150:153], v[222:225], v[12:15]
	v_mfma_f32_16x16x32_bf16 v[8:11], v[158:161], v[222:225], v[8:11]
	v_mfma_f32_16x16x32_bf16 v[60:63], v[154:157], v[198:201], v[60:63]
	v_mfma_f32_16x16x32_bf16 v[56:59], v[162:165], v[198:201], v[56:59]
	v_mfma_f32_16x16x32_bf16 v[44:47], v[154:157], v[206:209], v[44:47]
	v_mfma_f32_16x16x32_bf16 v[40:43], v[162:165], v[206:209], v[40:43]
	v_mfma_f32_16x16x32_bf16 v[28:31], v[154:157], v[218:221], v[28:31]
	v_mfma_f32_16x16x32_bf16 v[24:27], v[162:165], v[218:221], v[24:27]
	v_mfma_f32_16x16x32_bf16 v[12:15], v[154:157], v[226:229], v[12:15]
	v_mfma_f32_16x16x32_bf16 v[8:11], v[162:165], v[226:229], v[8:11]
	s_cmp_eq_u32 s10, 7
	s_cbranch_scc1 .Lp1_skip1
	v_mfma_f32_16x16x32_bf16 v[52:55], v[178:181], v[194:197], v[52:55]
	v_mfma_f32_16x16x32_bf16 v[48:51], v[186:189], v[194:197], v[48:51]
	v_mfma_f32_16x16x32_bf16 v[36:39], v[178:181], v[202:205], v[36:39]
	v_mfma_f32_16x16x32_bf16 v[32:35], v[186:189], v[202:205], v[32:35]
	v_mfma_f32_16x16x32_bf16 v[20:23], v[178:181], v[214:217], v[20:23]
	v_mfma_f32_16x16x32_bf16 v[16:19], v[186:189], v[214:217], v[16:19]
	v_mfma_f32_16x16x32_bf16 v[4:7], v[178:181], v[222:225], v[4:7]
	v_mfma_f32_16x16x32_bf16 v[0:3], v[186:189], v[222:225], v[0:3]
	v_mfma_f32_16x16x32_bf16 v[52:55], v[182:185], v[198:201], v[52:55]
	v_mfma_f32_16x16x32_bf16 v[48:51], v[190:193], v[198:201], v[48:51]
	v_mfma_f32_16x16x32_bf16 v[36:39], v[182:185], v[206:209], v[36:39]
	v_mfma_f32_16x16x32_bf16 v[32:35], v[190:193], v[206:209], v[32:35]
	v_mfma_f32_16x16x32_bf16 v[20:23], v[182:185], v[218:221], v[20:23]
	v_mfma_f32_16x16x32_bf16 v[16:19], v[190:193], v[218:221], v[16:19]
	v_mfma_f32_16x16x32_bf16 v[4:7], v[182:185], v[226:229], v[4:7]
	v_mfma_f32_16x16x32_bf16 v[0:3], v[190:193], v[226:229], v[0:3]
; #define G_STAGE(bufoff, gbase, v0, v1) do { \
;         __builtin_amdgcn_global_load_lds((const unsigned*)((const char*)(gbase) + (v0)), (LAS unsigned*)(lds + (bufoff) + ldsw), 16, 0, 0); \
;         __builtin_amdgcn_global_load_lds((const unsigned*)((const char*)(gbase) + (v1)), (LAS unsigned*)(lds + (bufoff) + ldsw + 8192), 16, 0, 0); } while (0)
; #define G_LDA(dst, b, h) do { _Pragma("unroll") for (int m = 0; m < 4; ++m) _Pragma("unroll") for (int k = 0; k < 2; ++k) dst[m][k] = *(const LAS bf16x8*)(lds + G_SA(b, h) + aoff + m * 2048 + k * 1024); } while (0)
; #define G_LDB(dst, b, h) do { _Pragma("unroll") for (int n = 0; n < 2; ++n) _Pragma("unroll") for (int k = 0; k < 2; ++k) dst[n][k] = *(const LAS bf16x8*)(lds + G_SB(b, h) + boff + n * 2048 + k * 1024); } while (0)
; #define G_MMA(ai, bj, At, Bt) do { __builtin_amdgcn_s_setprio(1); _Pragma("unroll") for (int m = 0; m < 4; ++m) _Pragma("unroll") for (int n = 0; n < 2; ++n) _Pragma("unroll") for (int k = 0; k < 2; ++k) \
;         acc[ai][bj][m][n] = __builtin_amdgcn_mfma_f32_16x16x32_bf16(Bt[n][k], At[m][k], acc[ai][bj][m][n], 0, 0, 0); __builtin_amdgcn_s_setprio(0); } while (0)
; #define G_WAIT_V(n) asm volatile("s_waitcnt vmcnt(" #n ")" ::: "memory")
; #define G_WAIT_L(n) asm volatile("s_waitcnt lgkmcnt(" #n ")" ::: "memory")
; #define G_BAR __builtin_amdgcn_s_barrier()
; #define G_SCHED __builtin_amdgcn_sched_barrier(0)
; template <class Epi, class Sched>
; __device__ __forceinline__ void gemm_phase(LAS unsigned char* lds, const Sched& S, const Epi& E) {
;     ...
;             G_LDB(B0, 1, 0); G_LDB(B1, 1, 1); G_SCHED; G_LDA(At, 1, 0); G_STAGE(G_SA(0, 1), a2 + h2, v20, v21);
;             G_WAIT_V(8); G_WAIT_L(0); G_BAR; G_MMA(0, 0, At, B0); G_MMA(0, 1, At, B1); G_BAR; G_SCHED;
.Lp1_skip1:
	s_setprio 0
	s_barrier
	s_add_i32 s68, 0, 0x18000
	v_add_u32_e32 v136, s68, v168
	s_add_i32 s69, 0, 0x1c000
	ds_read_b128 v[150:153], v136
	ds_read_b128 v[154:157], v136 offset:1024
	ds_read_b128 v[158:161], v136 offset:2048
	ds_read_b128 v[162:165], v136 offset:3072
	v_add_u32_e32 v136, s69, v168
	ds_read_b128 v[178:181], v136
	ds_read_b128 v[182:185], v136 offset:1024
	ds_read_b128 v[186:189], v136 offset:2048
	ds_read_b128 v[190:193], v136 offset:3072
	s_add_u32 s46, s46, 0x80000
	s_addc_u32 s47, s47, 0
	s_mov_b32 m0, s45
	v_lshl_add_u64 v[236:237], s[46:47], 0, v[132:133]
	ds_read_b128 v[194:197], v176 offset:32768
	ds_read_b128 v[198:201], v176 offset:33792
	ds_read_b128 v[202:205], v176 offset:34816
	ds_read_b128 v[206:209], v176 offset:35840
	ds_read_b128 v[214:217], v176 offset:36864
	ds_read_b128 v[218:221], v176 offset:37888
	ds_read_b128 v[222:225], v176 offset:38912
	ds_read_b128 v[226:229], v176 offset:39936
	global_load_lds_dwordx4 v[236:237], off
	v_lshl_add_u64 v[236:237], s[46:47], 0, v[134:135]
	s_mov_b32 m0, s86
	s_nop 0
	global_load_lds_dwordx4 v[236:237], off
	s_waitcnt vmcnt(8)
	s_waitcnt lgkmcnt(0)
	s_barrier
	s_setprio 1
	s_waitcnt lgkmcnt(0)
	v_mfma_f32_16x16x32_bf16 v[124:127], v[150:153], v[194:197], v[124:127]
	v_mfma_f32_16x16x32_bf16 v[120:123], v[158:161], v[194:197], v[120:123]
	v_mfma_f32_16x16x32_bf16 v[108:111], v[150:153], v[202:205], v[108:111]
	v_mfma_f32_16x16x32_bf16 v[104:107], v[158:161], v[202:205], v[104:107]
	v_mfma_f32_16x16x32_bf16 v[92:95], v[150:153], v[214:217], v[92:95]
	v_mfma_f32_16x16x32_bf16 v[88:91], v[158:161], v[214:217], v[88:91]
	v_mfma_f32_16x16x32_bf16 v[76:79], v[150:153], v[222:225], v[76:79]
	v_mfma_f32_16x16x32_bf16 v[72:75], v[158:161], v[222:225], v[72:75]
	v_mfma_f32_16x16x32_bf16 v[124:127], v[154:157], v[198:201], v[124:127]
	v_mfma_f32_16x16x32_bf16 v[120:123], v[162:165], v[198:201], v[120:123]
	v_mfma_f32_16x16x32_bf16 v[108:111], v[154:157], v[206:209], v[108:111]
	v_mfma_f32_16x16x32_bf16 v[104:107], v[162:165], v[206:209], v[104:107]
	v_mfma_f32_16x16x32_bf16 v[92:95], v[154:157], v[218:221], v[92:95]
	v_mfma_f32_16x16x32_bf16 v[88:91], v[162:165], v[218:221], v[88:91]
	v_mfma_f32_16x16x32_bf16 v[76:79], v[154:157], v[226:229], v[76:79]
	v_mfma_f32_16x16x32_bf16 v[72:75], v[162:165], v[226:229], v[72:75]
	s_cmp_eq_u32 s10, 7
	s_cbranch_scc1 .Lp1_skip2
	v_mfma_f32_16x16x32_bf16 v[116:119], v[178:181], v[194:197], v[116:119]
	v_mfma_f32_16x16x32_bf16 v[112:115], v[186:189], v[194:197], v[112:115]
	v_mfma_f32_16x16x32_bf16 v[100:103], v[178:181], v[202:205], v[100:103]
	v_mfma_f32_16x16x32_bf16 v[96:99], v[186:189], v[202:205], v[96:99]
	v_mfma_f32_16x16x32_bf16 v[84:87], v[178:181], v[214:217], v[84:87]
	v_mfma_f32_16x16x32_bf16 v[80:83], v[186:189], v[214:217], v[80:83]
	v_mfma_f32_16x16x32_bf16 v[68:71], v[178:181], v[222:225], v[68:71]
	v_mfma_f32_16x16x32_bf16 v[64:67], v[186:189], v[222:225], v[64:67]
	v_mfma_f32_16x16x32_bf16 v[116:119], v[182:185], v[198:201], v[116:119]
	v_mfma_f32_16x16x32_bf16 v[112:115], v[190:193], v[198:201], v[112:115]
	v_mfma_f32_16x16x32_bf16 v[100:103], v[182:185], v[206:209], v[100:103]
	v_mfma_f32_16x16x32_bf16 v[96:99], v[190:193], v[206:209], v[96:99]
	v_mfma_f32_16x16x32_bf16 v[84:87], v[182:185], v[218:221], v[84:87]
	v_mfma_f32_16x16x32_bf16 v[80:83], v[190:193], v[218:221], v[80:83]
	v_mfma_f32_16x16x32_bf16 v[68:71], v[182:185], v[226:229], v[68:71]
	v_mfma_f32_16x16x32_bf16 v[64:67], v[190:193], v[226:229], v[64:67]
; #define G_STAGE(bufoff, gbase, v0, v1) do { \
;         __builtin_amdgcn_global_load_lds((const unsigned*)((const char*)(gbase) + (v0)), (LAS unsigned*)(lds + (bufoff) + ldsw), 16, 0, 0); \
;         __builtin_amdgcn_global_load_lds((const unsigned*)((const char*)(gbase) + (v1)), (LAS unsigned*)(lds + (bufoff) + ldsw + 8192), 16, 0, 0); } while (0)
; #define G_LDA(dst, b, h) do { _Pragma("unroll") for (int m = 0; m < 4; ++m) _Pragma("unroll") for (int k = 0; k < 2; ++k) dst[m][k] = *(const LAS bf16x8*)(lds + G_SA(b, h) + aoff + m * 2048 + k * 1024); } while (0)
; #define G_MMA(ai, bj, At, Bt) do { __builtin_amdgcn_s_setprio(1); _Pragma("unroll") for (int m = 0; m < 4; ++m) _Pragma("unroll") for (int n = 0; n < 2; ++n) _Pragma("unroll") for (int k = 0; k < 2; ++k) \
;         acc[ai][bj][m][n] = __builtin_amdgcn_mfma_f32_16x16x32_bf16(Bt[n][k], At[m][k], acc[ai][bj][m][n], 0, 0, 0); __builtin_amdgcn_s_setprio(0); } while (0)
; #define G_WAIT_V(n) asm volatile("s_waitcnt vmcnt(" #n ")" ::: "memory")
; #define G_WAIT_L(n) asm volatile("s_waitcnt lgkmcnt(" #n ")" ::: "memory")
; #define G_BAR __builtin_amdgcn_s_barrier()
; #define G_SCHED __builtin_amdgcn_sched_barrier(0)
; template <class Epi, class Sched>
; __device__ __forceinline__ void gemm_phase(LAS unsigned char* lds, const Sched& S, const Epi& E) {
;     ...
;             G_LDA(At, 1, 1); G_STAGE(G_SB(1, 0), b3, vb0, vb1); G_STAGE(G_SB(1, 1), b3 + hstepB, vb0, vb1); G_STAGE(G_SA(1, 0), a3, v20, v21);
;             G_WAIT_V(8); G_WAIT_L(0); G_BAR; G_MMA(1, 0, At, B0); G_MMA(1, 1, At, B1); G_BAR; G_SCHED;
;         }
;         if (wr == 0) G_BAR;
.Lp1_skip2:
	s_setprio 0
	s_barrier
	s_add_i32 s46, s68, s24
	v_lshl_add_u64 v[210:211], v[210:211], 0, s[54:55]
	s_mov_b32 m0, s46
	ds_read_b128 v[194:197], v176 offset:49152
	ds_read_b128 v[198:201], v176 offset:50176
	ds_read_b128 v[202:205], v176 offset:51200
	ds_read_b128 v[206:209], v176 offset:52224
	ds_read_b128 v[214:217], v176 offset:53248
	ds_read_b128 v[218:221], v176 offset:54272
	ds_read_b128 v[222:225], v176 offset:55296
	ds_read_b128 v[226:229], v176 offset:56320
	global_load_lds_dwordx4 v[210:211], off
	s_add_i32 m0, s46, 0x2000
	s_add_u32 s12, s12, 0x80080
	v_lshl_add_u64 v[210:211], v[230:231], 0, s[54:55]
	s_addc_u32 s13, s13, 0
	s_add_i32 s46, s69, s24
	global_load_lds_dwordx4 v[210:211], off
	v_lshl_add_u64 v[210:211], s[12:13], 0, v[132:133]
	s_mov_b32 m0, s46
	s_nop 0
	global_load_lds_dwordx4 v[210:211], off
	v_lshl_add_u64 v[210:211], s[12:13], 0, v[134:135]
	s_add_i32 m0, s46, 0x2000
	s_nop 0
	global_load_lds_dwordx4 v[210:211], off
	v_lshl_add_u64 v[210:211], v[232:233], 0, s[54:55]
	s_mov_b32 m0, s17
	s_nop 0
	global_load_lds_dwordx4 v[210:211], off
	v_lshl_add_u64 v[210:211], v[234:235], 0, s[54:55]
	s_mov_b32 m0, s52
	s_nop 0
	global_load_lds_dwordx4 v[210:211], off
	s_waitcnt vmcnt(8)
	s_waitcnt lgkmcnt(0)
	s_barrier
	s_setprio 1
	s_waitcnt lgkmcnt(0)
	v_mfma_f32_16x16x32_bf16 v[60:63], v[150:153], v[194:197], v[60:63]
	v_mfma_f32_16x16x32_bf16 v[56:59], v[158:161], v[194:197], v[56:59]
	v_mfma_f32_16x16x32_bf16 v[44:47], v[150:153], v[202:205], v[44:47]
	v_mfma_f32_16x16x32_bf16 v[40:43], v[158:161], v[202:205], v[40:43]
	v_mfma_f32_16x16x32_bf16 v[28:31], v[150:153], v[214:217], v[28:31]
	v_mfma_f32_16x16x32_bf16 v[24:27], v[158:161], v[214:217], v[24:27]
	v_mfma_f32_16x16x32_bf16 v[12:15], v[150:153], v[222:225], v[12:15]
	v_mfma_f32_16x16x32_bf16 v[8:11], v[158:161], v[222:225], v[8:11]
	v_mfma_f32_16x16x32_bf16 v[60:63], v[154:157], v[198:201], v[60:63]
	v_mfma_f32_16x16x32_bf16 v[56:59], v[162:165], v[198:201], v[56:59]
	v_mfma_f32_16x16x32_bf16 v[44:47], v[154:157], v[206:209], v[44:47]
	v_mfma_f32_16x16x32_bf16 v[40:43], v[162:165], v[206:209], v[40:43]
	v_mfma_f32_16x16x32_bf16 v[28:31], v[154:157], v[218:221], v[28:31]
	v_mfma_f32_16x16x32_bf16 v[24:27], v[162:165], v[218:221], v[24:27]
	v_mfma_f32_16x16x32_bf16 v[12:15], v[154:157], v[226:229], v[12:15]
	v_mfma_f32_16x16x32_bf16 v[8:11], v[162:165], v[226:229], v[8:11]
	s_cmp_eq_u32 s10, 7
	s_cbranch_scc1 .Lp1_skip3
	v_mfma_f32_16x16x32_bf16 v[52:55], v[178:181], v[194:197], v[52:55]
	v_mfma_f32_16x16x32_bf16 v[48:51], v[186:189], v[194:197], v[48:51]
	v_mfma_f32_16x16x32_bf16 v[36:39], v[178:181], v[202:205], v[36:39]
	v_mfma_f32_16x16x32_bf16 v[32:35], v[186:189], v[202:205], v[32:35]
	v_mfma_f32_16x16x32_bf16 v[20:23], v[178:181], v[214:217], v[20:23]
	v_mfma_f32_16x16x32_bf16 v[16:19], v[186:189], v[214:217], v[16:19]
	v_mfma_f32_16x16x32_bf16 v[4:7], v[178:181], v[222:225], v[4:7]
	v_mfma_f32_16x16x32_bf16 v[0:3], v[186:189], v[222:225], v[0:3]
	v_mfma_f32_16x16x32_bf16 v[52:55], v[182:185], v[198:201], v[52:55]
	v_mfma_f32_16x16x32_bf16 v[48:51], v[190:193], v[198:201], v[48:51]
	v_mfma_f32_16x16x32_bf16 v[36:39], v[182:185], v[206:209], v[36:39]
	v_mfma_f32_16x16x32_bf16 v[32:35], v[190:193], v[206:209], v[32:35]
	v_mfma_f32_16x16x32_bf16 v[20:23], v[182:185], v[218:221], v[20:23]
	v_mfma_f32_16x16x32_bf16 v[16:19], v[190:193], v[218:221], v[16:19]
	v_mfma_f32_16x16x32_bf16 v[4:7], v[182:185], v[226:229], v[4:7]
	v_mfma_f32_16x16x32_bf16 v[0:3], v[190:193], v[226:229], v[0:3]
.Lp1_skip3:
	s_setprio 0
	s_barrier
	s_add_i32 s63, s63, 2
	s_add_u32 s8, s8, 0x100
	s_addc_u32 s9, s9, 0
	s_add_u32 s50, s50, 0x100
	s_addc_u32 s61, s61, 0
	s_cmp_gt_u32 s63, 29
	s_cbranch_scc0 .LBB0_184
	s_and_b64 vcc, exec, s[56:57]
	s_cbranch_vccz .LBB0_187
	s_barrier
